# stack2 + CONV_KT 24 (24 deferred weight blocks per wave converted in the idle CUs of the in-projection's last round)
# baseline (speedup 1.0000x reference)
.LBB8_256:
	s_cmp_lt_i32 s92, 3
	s_mul_i32 s59, s59, s68
	s_cselect_b64 s[6:7], -1, 0
	s_sub_i32 s8, s58, s59
	s_sub_i32 s9, s8, s68
	s_cmp_ge_u32 s8, s68
	s_cselect_b32 s8, s9, s8
	s_sub_i32 s9, s8, s68
	s_cmp_ge_u32 s8, s68
	s_cselect_b32 s8, s9, s8
	s_xor_b32 s38, s8, s56
	s_sub_i32 s39, s38, s56
	s_mul_i32 s8, s39, 0xc0
	s_and_b32 s8, s8, 0xffffff00
	s_cmpk_lt_i32 s39, 0x80
	v_readlane_b32 s10, v254, 2
	s_cselect_b32 s67, s8, 0x6000
	v_readlane_b32 s11, v254, 3
	s_add_u32 s68, s10, 0x200000
	s_addc_u32 s69, s11, 0
	s_add_u32 s54, s10, 0x800000
	s_addc_u32 s55, s11, 0
	s_add_u32 s36, s10, 0xc800000
	s_addc_u32 s37, s11, 0
	s_add_u32 s90, s10, 0x2a000000
	s_addc_u32 s91, s11, 0
	s_add_u32 s8, s10, 0x2b000000
	s_addc_u32 s9, s11, 0
	v_writelane_b32 v254, s8, 41
	s_nop 1
	v_writelane_b32 v254, s9, 42
	s_add_u32 s8, s10, 0x2c000000
	s_addc_u32 s9, s11, 0
	v_writelane_b32 v254, s8, 43
	s_nop 1
	v_writelane_b32 v254, s9, 44
	s_add_u32 s8, s10, 0x2e000000
	s_addc_u32 s9, s11, 0
	v_writelane_b32 v254, s8, 45
	s_add_u32 s88, s10, 0x36000000
	s_addc_u32 s89, s11, 0
	v_writelane_b32 v254, s9, 46
	s_and_b64 s[34:35], s[6:7], s[0:1]
	s_mov_b64 s[0:1], s[92:93]
	v_writelane_b32 v254, s0, 47
	s_andn2_b64 vcc, exec, s[34:35]
	s_nop 0
	v_writelane_b32 v254, s1, 48
	v_writelane_b32 v254, s2, 49
	v_writelane_b32 v254, s3, 50
	v_writelane_b32 v254, s68, 51
	s_nop 1
	v_writelane_b32 v254, s69, 52
	s_cbranch_vccnz .LBB8_357
	v_readlane_b32 s0, v254, 40
	s_waitcnt vmcnt(13) lgkmcnt(2)
	v_mbcnt_lo_u32_b32 v10, -1, 0
	v_mbcnt_hi_u32_b32 v10, -1, v10
	s_cmpk_gt_i32 s2, 0x99f
	s_waitcnt lgkmcnt(0)
	v_add_u32_e32 v0, s0, v10
	s_nop 0
	v_readfirstlane_b32 s1, v0
	s_cbranch_scc1 .LBB8_279
	v_lshlrev_b32_e32 v1, 4, v0
	v_add_u32_e32 v2, 0x2000, v1
	v_ashrrev_i32_e32 v3, 31, v2
	v_lshrrev_b32_e32 v3, 22, v3
	v_add_u32_e32 v3, v2, v3
	v_ashrrev_i32_e32 v8, 10, v3
	v_mul_i32_i24_e32 v3, 0x400, v8
	v_sub_u32_e32 v2, v2, v3
	v_lshrrev_b32_e32 v3, 4, v2
	v_bitop3_b32 v2, v3, v2, 32 bitop3:0x6c
	v_ashrrev_i32_e32 v3, 31, v2
	v_lshrrev_b32_e32 v3, 26, v3
	v_add_u32_e32 v3, v2, v3
	v_lshlrev_b32_e32 v4, 3, v8
	v_ashrrev_i32_e32 v9, 6, v3
	v_and_b32_e32 v4, -16, v4
	v_add_u32_e32 v4, v9, v4
	v_and_b32_e32 v5, 3, v9
	s_mov_b32 s0, 0x7ffe0
	v_lshrrev_b32_e32 v6, 2, v4
	v_lshlrev_b32_e32 v7, 1, v4
	v_and_b32_e32 v3, 0xc0, v3
	v_and_or_b32 v5, v4, s0, v5
	v_and_b32_e32 v6, 4, v6
	v_and_b32_e32 v7, 24, v7
	v_sub_u32_e32 v2, v2, v3
	v_mov_b32_e32 v3, 1
	v_or3_b32 v5, v5, v6, v7
	v_lshlrev_b32_e32 v6, 5, v8
	v_ashrrev_i16_sdwa v2, v3, sext(v2) dst_sel:DWORD dst_unused:UNUSED_PAD src0_sel:DWORD src1_sel:BYTE_0
	v_and_b32_e32 v6, 32, v6
	v_bfe_i32 v11, v2, 0, 16
	v_add_lshl_u32 v2, v6, v11, 1
	v_lshl_add_u32 v128, v5, 13, v2
	v_lshl_add_u32 v130, v4, 13, v2
	v_bfe_i32 v2, v0, 27, 1
	v_lshrrev_b32_e32 v2, 22, v2
	v_add_u32_e32 v2, v1, v2
	v_and_b32_e32 v2, 0xfffffc00, v2
	v_sub_u32_e32 v1, v1, v2
	v_lshrrev_b32_e32 v2, 4, v1
	v_ashrrev_i32_e32 v4, 31, v0
	v_bitop3_b32 v1, v2, v1, 32 bitop3:0x6c
	v_lshrrev_b32_e32 v4, 26, v4
	v_ashrrev_i32_e32 v2, 31, v1
	v_add_u32_e32 v0, v0, v4
	v_lshrrev_b32_e32 v2, 26, v2
	s_waitcnt vmcnt(12)
	v_ashrrev_i32_e32 v13, 6, v0
	v_add_u32_e32 v2, v1, v2
	v_lshlrev_b32_e32 v0, 3, v13
	v_ashrrev_i32_e32 v12, 6, v2
	v_and_b32_e32 v0, -16, v0
	v_add_u32_e32 v0, v12, v0
	v_and_b32_e32 v4, 3, v12
	s_ashr_i32 s58, s2, 31
	v_and_or_b32 v4, v0, s0, v4
	s_lshr_b32 s0, s58, 29
	s_add_i32 s0, s2, s0
	s_ashr_i32 s8, s1, 6
	s_ashr_i32 s6, s0, 3
	s_and_b32 s0, s0, -8
	s_ashr_i32 s10, s1, 8
	s_lshl_b32 s57, s8, 10
	s_sub_i32 s0, s2, s0
	s_cmp_lt_i32 s0, 0
	s_movk_i32 s59, 0x135
	s_cselect_b32 s7, s59, 0x134
	s_mul_i32 s0, s0, s7
	s_add_i32 s0, s0, s6
	s_mul_hi_i32 s6, s0, 0x3531dec1
	s_lshr_b32 s7, s6, 31
	s_ashr_i32 s6, s6, 7
	s_add_i32 s6, s6, s7
	s_lshl_b32 s7, s6, 3
	s_mulk_i32 s6, 0x268
	s_sub_i32 s6, s0, s6
	s_sext_i32_i16 s0, s6
	s_bfe_u32 s0, s0, 0x3001c
	s_add_i32 s9, s6, s0
	s_sext_i32_i16 s0, s9
	s_and_b32 s9, s9, 0xfff8
	s_sub_i32 s6, s6, s9
	s_sext_i32_i16 s6, s6
	v_lshrrev_b32_e32 v5, 2, v0
	v_lshlrev_b32_e32 v6, 1, v0
	v_and_b32_e32 v2, 0xc0, v2
	s_lshr_b32 s0, s0, 3
	s_add_i32 s68, s7, s6
	v_and_b32_e32 v5, 4, v5
	v_and_b32_e32 v6, 24, v6
	v_sub_u32_e32 v1, v1, v2
	s_ashr_i32 s69, s68, 31
	s_bfe_i64 s[12:13], s[0:1], 0x100000
	v_or3_b32 v4, v4, v5, v6
	v_lshlrev_b32_e32 v5, 5, v13
	v_ashrrev_i16_sdwa v1, v3, sext(v1) dst_sel:DWORD dst_unused:UNUSED_PAD src0_sel:DWORD src1_sel:BYTE_0
	s_lshl_b64 s[6:7], s[68:69], 21
	s_lshl_b64 s[12:13], s[12:13], 21
	v_and_b32_e32 v5, 32, v5
	v_bfe_i32 v14, v1, 0, 16
	s_add_u32 s28, s4, s12
	v_add_lshl_u32 v1, v5, v14, 1
	s_addc_u32 s29, s5, s13
	s_add_i32 s69, s57, 0
	v_lshl_add_u32 v132, v4, 13, v1
	s_add_i32 m0, s69, 0x10000
	v_lshl_add_u32 v134, v0, 13, v1
	global_load_lds_dwordx4 v132, s[28:29]
	s_add_i32 m0, s69, 0x12000
	s_add_u32 s12, s28, 0x100000
	global_load_lds_dwordx4 v128, s[28:29]
	s_addc_u32 s13, s29, 0
	s_add_i32 m0, s69, 0x14000
	v_mov_b32_e32 v133, 0
	global_load_lds_dwordx4 v132, s[12:13]
	s_add_i32 m0, s69, 0x16000
	s_add_u32 s70, s54, s6
	s_addc_u32 s71, s55, s7
	s_add_i32 s74, s69, 0x2000
	global_load_lds_dwordx4 v128, s[12:13]
	s_mov_b32 m0, s69
	s_add_u32 s6, s70, 0x100000
	global_load_lds_dwordx4 v134, s[70:71]
	s_mov_b32 m0, s74
	s_addc_u32 s7, s71, 0
	s_add_i32 s75, s69, 0x4000
	global_load_lds_dwordx4 v130, s[70:71]
	s_mov_b32 m0, s75
	s_add_i32 s76, s69, 0x6000
	global_load_lds_dwordx4 v134, s[6:7]
	s_mov_b32 m0, s76
	v_mov_b32_e32 v129, v133
	global_load_lds_dwordx4 v130, s[6:7]
	v_mov_b32_e32 v135, v133
	v_mov_b32_e32 v131, v133
	s_cmp_eq_u32 s10, 1
	s_mov_b32 s77, 0
	v_lshl_add_u64 v[6:7], s[28:29], 0, v[132:133]
	v_lshl_add_u64 v[4:5], s[28:29], 0, v[128:129]
	v_lshl_add_u64 v[0:1], s[70:71], 0, v[134:135]
	s_cselect_b64 s[6:7], -1, 0
	s_cmp_lg_u32 s10, 1
	v_lshl_add_u64 v[2:3], s[70:71], 0, v[130:131]
	s_cbranch_scc1 .LBB8_260
	s_barrier
